# K-loops: the compiler's redundant lgkmcnt(0) at each MFMA burst head moved in front of the opening barrier (burst starts with s_setprio + MFMA; byte layout of the MFMAs unchanged)
# speedup vs baseline: 1.0124x; 1.0124x over previous
; #define PG8_STAGE(bufoff, gbase, voff) do { _Pragma("unroll") for (int _i = 0; _i < 2; ++_i) \
;         __builtin_amdgcn_global_load_lds((const unsigned*)((const char*)(gbase) + (voff)[_i]), (LAS unsigned*)(lds + (bufoff) + ldsw + _i * 8192), 16, 0, 0); } while (0)
; #define PG8_LDA(dst, b, h) do { _Pragma("unroll") for (int m = 0; m < 4; ++m) _Pragma("unroll") for (int k = 0; k < 2; ++k) dst[m][k] = *(const LAS bf16x8*)(lds + PG8_SA(b, h) + aoff + m * 2048 + k * 1024); } while (0)
; #define PG8_LDB(dst, b, h) do { _Pragma("unroll") for (int n = 0; n < 2; ++n) _Pragma("unroll") for (int k = 0; k < 2; ++k) dst[n][k] = *(const LAS bf16x8*)(lds + PG8_SB(b, h) + boff + n * 2048 + k * 1024); } while (0)
; #define PG8_MMA(ai, bj, At, Bt) do { __builtin_amdgcn_s_setprio(1); _Pragma("unroll") for (int m = 0; m < 4; ++m) _Pragma("unroll") for (int n = 0; n < 2; ++n) _Pragma("unroll") for (int k = 0; k < 2; ++k) \
;         acc[ai][bj][m][n] = __builtin_amdgcn_mfma_f32_16x16x32_bf16(Bt[n][k], At[m][k], acc[ai][bj][m][n], 0, 0, 0); __builtin_amdgcn_s_setprio(0); } while (0)
; #define PG8_WAIT_V(n) asm volatile("s_waitcnt vmcnt(" #n ")" ::: "memory")
; #define PG8_WAIT_L(n) asm volatile("s_waitcnt lgkmcnt(" #n ")" ::: "memory")
; #define PG8_BAR __builtin_amdgcn_s_barrier()
; #define PG8_SCHED __builtin_amdgcn_sched_barrier(0)
;     ...
;             PG8_LDB(B0, 0, 0); PG8_LDB(B1, 0, 1); PG8_SCHED; PG8_LDA(At, 0, 0); PG8_STAGE(PG8_SA(1, 1), a1 + hstepA, voffA);
;             PG8_WAIT_V(8); PG8_WAIT_L(0); PG8_BAR; PG8_MMA(0, 0, At, B0); PG8_MMA(0, 1, At, B1); PG8_BAR; PG8_SCHED;
;             PG8_LDA(At, 0, 1); PG8_STAGE(PG8_SB(0, 0), b2, voffB); PG8_STAGE(PG8_SB(0, 1), b2 + hstepB, voffB); PG8_STAGE(PG8_SA(0, 0), a2, voffA);
;             PG8_WAIT_V(8); PG8_WAIT_L(0); PG8_BAR; PG8_MMA(1, 0, At, B0); PG8_MMA(1, 1, At, B1); PG8_BAR; PG8_SCHED;
;             PG8_LDB(B0, 1, 0); PG8_LDB(B1, 1, 1); PG8_SCHED; PG8_LDA(At, 1, 0); PG8_STAGE(PG8_SA(0, 1), a2 + hstepA, voffA);
;             PG8_WAIT_V(8); PG8_WAIT_L(0); PG8_BAR; PG8_MMA(0, 0, At, B0); PG8_MMA(0, 1, At, B1); PG8_BAR; PG8_SCHED;
.LBB0_159:
	s_add_i32 s38, s8, 2
	s_add_u32 s26, s12, s0
	s_addc_u32 s9, s13, s1
	s_add_i32 s27, 0, 0x10000
	s_cmp_eq_u32 s63, s8
	s_cselect_b32 s9, s18, s9
	s_cselect_b32 s8, s19, s26
	s_cselect_b64 vcc, -1, 0
	s_add_i32 s26, 0, 0x14000
	v_lshl_add_u64 v[150:151], v[188:189], 0, s[0:1]
	v_add_u32_e32 v146, s27, v226
	v_add_u32_e32 v162, s26, v226
	ds_read_b128 v[134:137], v146
	ds_read_b128 v[138:141], v146 offset:1024
	ds_read_b128 v[142:145], v146 offset:2048
	ds_read_b128 v[146:149], v146 offset:3072
	v_cndmask_b32_e32 v205, v151, v132, vcc
	v_cndmask_b32_e32 v204, v150, v133, vcc
	ds_read_b128 v[150:153], v162
	ds_read_b128 v[154:157], v162 offset:1024
	ds_read_b128 v[158:161], v162 offset:2048
	ds_read_b128 v[162:165], v162 offset:3072
	v_lshl_add_u64 v[212:213], s[12:13], 0, v[130:131]
	s_add_i32 m0, s20, 0xc000
	ds_read_b128 v[166:169], v227
	ds_read_b128 v[170:173], v227 offset:1024
	ds_read_b128 v[174:177], v227 offset:2048
	ds_read_b128 v[178:181], v227 offset:3072
	ds_read_b128 v[230:233], v227 offset:4096
	ds_read_b128 v[234:237], v227 offset:5120
	ds_read_b128 v[238:241], v227 offset:6144
	ds_read_b128 v[242:245], v227 offset:7168
	global_load_lds_dwordx4 v[212:213], off
	v_lshl_add_u64 v[212:213], s[12:13], 0, v[128:129]
	s_add_i32 m0, s20, 0xe000
	s_nop 0
	global_load_lds_dwordx4 v[212:213], off
	s_waitcnt vmcnt(8)
	s_waitcnt lgkmcnt(0)
	s_waitcnt lgkmcnt(0)
	s_barrier
	s_setprio 1
	v_mfma_f32_16x16x32_bf16 v[124:127], v[134:137], v[166:169], v[124:127]
	v_mfma_f32_16x16x32_bf16 v[0:3], v[142:145], v[166:169], v[0:3]
	v_mfma_f32_16x16x32_bf16 v[120:123], v[134:137], v[174:177], v[120:123]
	v_mfma_f32_16x16x32_bf16 v[116:119], v[142:145], v[174:177], v[116:119]
	v_mfma_f32_16x16x32_bf16 v[112:115], v[134:137], v[230:233], v[112:115]
	v_mfma_f32_16x16x32_bf16 v[108:111], v[142:145], v[230:233], v[108:111]
	v_mfma_f32_16x16x32_bf16 v[104:107], v[134:137], v[238:241], v[104:107]
	v_mfma_f32_16x16x32_bf16 v[4:7], v[142:145], v[238:241], v[4:7]
	v_mfma_f32_16x16x32_bf16 v[124:127], v[138:141], v[170:173], v[124:127]
	v_mfma_f32_16x16x32_bf16 v[0:3], v[146:149], v[170:173], v[0:3]
	v_mfma_f32_16x16x32_bf16 v[120:123], v[138:141], v[178:181], v[120:123]
	v_mfma_f32_16x16x32_bf16 v[116:119], v[146:149], v[178:181], v[116:119]
	v_mfma_f32_16x16x32_bf16 v[112:115], v[138:141], v[234:237], v[112:115]
	v_mfma_f32_16x16x32_bf16 v[108:111], v[146:149], v[234:237], v[108:111]
	v_mfma_f32_16x16x32_bf16 v[104:107], v[138:141], v[242:245], v[104:107]
	v_mfma_f32_16x16x32_bf16 v[4:7], v[146:149], v[242:245], v[4:7]
	s_setprio 0
	s_setprio 1
	v_mfma_f32_16x16x32_bf16 v[100:103], v[150:153], v[166:169], v[100:103]
	v_mfma_f32_16x16x32_bf16 v[96:99], v[158:161], v[166:169], v[96:99]
	v_mfma_f32_16x16x32_bf16 v[92:95], v[150:153], v[174:177], v[92:95]
	v_mfma_f32_16x16x32_bf16 v[88:91], v[158:161], v[174:177], v[88:91]
	v_mfma_f32_16x16x32_bf16 v[84:87], v[150:153], v[230:233], v[84:87]
	v_mfma_f32_16x16x32_bf16 v[80:83], v[158:161], v[230:233], v[80:83]
	v_mfma_f32_16x16x32_bf16 v[76:79], v[150:153], v[238:241], v[76:79]
	v_mfma_f32_16x16x32_bf16 v[72:75], v[158:161], v[238:241], v[72:75]
	v_mfma_f32_16x16x32_bf16 v[100:103], v[154:157], v[170:173], v[100:103]
	v_mfma_f32_16x16x32_bf16 v[96:99], v[162:165], v[170:173], v[96:99]
	v_mfma_f32_16x16x32_bf16 v[92:95], v[154:157], v[178:181], v[92:95]
	v_mfma_f32_16x16x32_bf16 v[88:91], v[162:165], v[178:181], v[88:91]
	v_mfma_f32_16x16x32_bf16 v[84:87], v[154:157], v[234:237], v[84:87]
	v_mfma_f32_16x16x32_bf16 v[80:83], v[162:165], v[234:237], v[80:83]
	v_mfma_f32_16x16x32_bf16 v[76:79], v[154:157], v[242:245], v[76:79]
	v_mfma_f32_16x16x32_bf16 v[72:75], v[162:165], v[242:245], v[72:75]
	s_setprio 0
	s_barrier
	s_add_i32 s27, s27, s11
	v_lshl_add_u64 v[212:213], v[204:205], 0, v[192:193]
	s_mov_b32 m0, s27
	ds_read_b128 v[166:169], v227 offset:16384
	ds_read_b128 v[170:173], v227 offset:17408
	ds_read_b128 v[174:177], v227 offset:18432
	ds_read_b128 v[178:181], v227 offset:19456
	ds_read_b128 v[230:233], v227 offset:20480
	ds_read_b128 v[234:237], v227 offset:21504
	ds_read_b128 v[238:241], v227 offset:22528
	ds_read_b128 v[242:245], v227 offset:23552
	global_load_lds_dwordx4 v[212:213], off
	v_lshl_add_u64 v[218:219], v[204:205], 0, v[196:197]
	s_add_i32 m0, s27, 0x2000
	v_lshl_add_u64 v[204:205], v[204:205], 0, v[198:199]
	s_add_i32 s26, s26, s11
	global_load_lds_dwordx4 v[218:219], off
	v_lshl_add_u64 v[246:247], v[204:205], 0, v[192:193]
	s_mov_b32 m0, s26
	v_lshl_add_u64 v[204:205], v[204:205], 0, v[196:197]
	global_load_lds_dwordx4 v[246:247], off
	s_add_i32 m0, s26, 0x2000
	v_lshl_add_u64 v[248:249], s[8:9], 0, v[190:191]
	global_load_lds_dwordx4 v[204:205], off
	s_mov_b32 m0, s20
	v_lshl_add_u64 v[250:251], s[8:9], 0, v[194:195]
	global_load_lds_dwordx4 v[248:249], off
	s_mov_b32 m0, s48
	s_nop 0
	global_load_lds_dwordx4 v[250:251], off
	s_waitcnt vmcnt(8)
	s_waitcnt lgkmcnt(0)
	s_waitcnt lgkmcnt(0)
	s_barrier
; #define PG8_STAGE(bufoff, gbase, voff) do { _Pragma("unroll") for (int _i = 0; _i < 2; ++_i) \
;         __builtin_amdgcn_global_load_lds((const unsigned*)((const char*)(gbase) + (voff)[_i]), (LAS unsigned*)(lds + (bufoff) + ldsw + _i * 8192), 16, 0, 0); } while (0)
; #define PG8_LDA(dst, b, h) do { _Pragma("unroll") for (int m = 0; m < 4; ++m) _Pragma("unroll") for (int k = 0; k < 2; ++k) dst[m][k] = *(const LAS bf16x8*)(lds + PG8_SA(b, h) + aoff + m * 2048 + k * 1024); } while (0)
; #define PG8_LDB(dst, b, h) do { _Pragma("unroll") for (int n = 0; n < 2; ++n) _Pragma("unroll") for (int k = 0; k < 2; ++k) dst[n][k] = *(const LAS bf16x8*)(lds + PG8_SB(b, h) + boff + n * 2048 + k * 1024); } while (0)
; #define PG8_MMA(ai, bj, At, Bt) do { __builtin_amdgcn_s_setprio(1); _Pragma("unroll") for (int m = 0; m < 4; ++m) _Pragma("unroll") for (int n = 0; n < 2; ++n) _Pragma("unroll") for (int k = 0; k < 2; ++k) \
;         acc[ai][bj][m][n] = __builtin_amdgcn_mfma_f32_16x16x32_bf16(Bt[n][k], At[m][k], acc[ai][bj][m][n], 0, 0, 0); __builtin_amdgcn_s_setprio(0); } while (0)
; #define PG8_WAIT_V(n) asm volatile("s_waitcnt vmcnt(" #n ")" ::: "memory")
; #define PG8_WAIT_L(n) asm volatile("s_waitcnt lgkmcnt(" #n ")" ::: "memory")
; #define PG8_BAR __builtin_amdgcn_s_barrier()
; #define PG8_SCHED __builtin_amdgcn_sched_barrier(0)
;     ...
;             PG8_WAIT_V(8); PG8_WAIT_L(0); PG8_BAR; PG8_MMA(1, 0, At, B0); PG8_MMA(1, 1, At, B1); PG8_BAR; PG8_SCHED;
;             PG8_LDB(B0, 1, 0); PG8_LDB(B1, 1, 1); PG8_SCHED; PG8_LDA(At, 1, 0); PG8_STAGE(PG8_SA(0, 1), a2 + hstepA, voffA);
;             PG8_WAIT_V(8); PG8_WAIT_L(0); PG8_BAR; PG8_MMA(0, 0, At, B0); PG8_MMA(0, 1, At, B1); PG8_BAR; PG8_SCHED;
	s_setprio 1
	v_mfma_f32_16x16x32_bf16 v[68:71], v[134:137], v[166:169], v[68:71]
	v_mfma_f32_16x16x32_bf16 v[8:11], v[142:145], v[166:169], v[8:11]
	v_mfma_f32_16x16x32_bf16 v[64:67], v[134:137], v[174:177], v[64:67]
	v_mfma_f32_16x16x32_bf16 v[60:63], v[142:145], v[174:177], v[60:63]
	v_mfma_f32_16x16x32_bf16 v[56:59], v[134:137], v[230:233], v[56:59]
	v_mfma_f32_16x16x32_bf16 v[52:55], v[142:145], v[230:233], v[52:55]
	v_mfma_f32_16x16x32_bf16 v[48:51], v[134:137], v[238:241], v[48:51]
	v_mfma_f32_16x16x32_bf16 v[12:15], v[142:145], v[238:241], v[12:15]
	v_mfma_f32_16x16x32_bf16 v[68:71], v[138:141], v[170:173], v[68:71]
	v_mfma_f32_16x16x32_bf16 v[8:11], v[146:149], v[170:173], v[8:11]
	v_mfma_f32_16x16x32_bf16 v[64:67], v[138:141], v[178:181], v[64:67]
	v_mfma_f32_16x16x32_bf16 v[60:63], v[146:149], v[178:181], v[60:63]
	v_mfma_f32_16x16x32_bf16 v[56:59], v[138:141], v[234:237], v[56:59]
	v_mfma_f32_16x16x32_bf16 v[52:55], v[146:149], v[234:237], v[52:55]
	v_mfma_f32_16x16x32_bf16 v[48:51], v[138:141], v[242:245], v[48:51]
	v_mfma_f32_16x16x32_bf16 v[12:15], v[146:149], v[242:245], v[12:15]
	s_setprio 0
	s_setprio 1
	v_mfma_f32_16x16x32_bf16 v[44:47], v[150:153], v[166:169], v[44:47]
	v_mfma_f32_16x16x32_bf16 v[40:43], v[158:161], v[166:169], v[40:43]
	v_mfma_f32_16x16x32_bf16 v[36:39], v[150:153], v[174:177], v[36:39]
	v_mfma_f32_16x16x32_bf16 v[32:35], v[158:161], v[174:177], v[32:35]
	v_mfma_f32_16x16x32_bf16 v[28:31], v[150:153], v[230:233], v[28:31]
	v_mfma_f32_16x16x32_bf16 v[24:27], v[158:161], v[230:233], v[24:27]
	v_mfma_f32_16x16x32_bf16 v[20:23], v[150:153], v[238:241], v[20:23]
	v_mfma_f32_16x16x32_bf16 v[16:19], v[158:161], v[238:241], v[16:19]
	v_mfma_f32_16x16x32_bf16 v[44:47], v[154:157], v[170:173], v[44:47]
	v_mfma_f32_16x16x32_bf16 v[40:43], v[162:165], v[170:173], v[40:43]
	v_mfma_f32_16x16x32_bf16 v[36:39], v[154:157], v[178:181], v[36:39]
	v_mfma_f32_16x16x32_bf16 v[32:35], v[162:165], v[178:181], v[32:35]
	v_mfma_f32_16x16x32_bf16 v[28:31], v[154:157], v[234:237], v[28:31]
	v_mfma_f32_16x16x32_bf16 v[24:27], v[162:165], v[234:237], v[24:27]
	v_mfma_f32_16x16x32_bf16 v[20:23], v[154:157], v[242:245], v[20:23]
	v_mfma_f32_16x16x32_bf16 v[16:19], v[162:165], v[242:245], v[16:19]
	s_setprio 0
	s_barrier
	s_add_i32 s26, 0, 0x18000
	s_add_i32 s27, 0, 0x1c000
	v_add_u32_e32 v146, s26, v226
	v_add_u32_e32 v162, s27, v226
	ds_read_b128 v[134:137], v146
	ds_read_b128 v[138:141], v146 offset:1024
	ds_read_b128 v[142:145], v146 offset:2048
	ds_read_b128 v[146:149], v146 offset:3072
	ds_read_b128 v[150:153], v162
	ds_read_b128 v[154:157], v162 offset:1024
	ds_read_b128 v[158:161], v162 offset:2048
	ds_read_b128 v[162:165], v162 offset:3072
	s_add_u32 s8, s8, s10
	s_addc_u32 s9, s9, 0
	s_mov_b32 m0, s51
	v_lshl_add_u64 v[214:215], s[8:9], 0, v[190:191]
	ds_read_b128 v[166:169], v227 offset:32768
	ds_read_b128 v[170:173], v227 offset:33792
	ds_read_b128 v[174:177], v227 offset:34816
	ds_read_b128 v[178:181], v227 offset:35840
	ds_read_b128 v[230:233], v227 offset:36864
	ds_read_b128 v[234:237], v227 offset:37888
	ds_read_b128 v[238:241], v227 offset:38912
	ds_read_b128 v[242:245], v227 offset:39936
	global_load_lds_dwordx4 v[214:215], off
	v_lshl_add_u64 v[214:215], s[8:9], 0, v[194:195]
	s_mov_b32 m0, s62
	s_nop 0
	global_load_lds_dwordx4 v[214:215], off
	s_waitcnt vmcnt(8)
	s_waitcnt lgkmcnt(0)
	s_waitcnt lgkmcnt(0)
	s_barrier
	s_setprio 1
	v_mfma_f32_16x16x32_bf16 v[124:127], v[134:137], v[166:169], v[124:127]
	v_mfma_f32_16x16x32_bf16 v[0:3], v[142:145], v[166:169], v[0:3]
	v_mfma_f32_16x16x32_bf16 v[120:123], v[134:137], v[174:177], v[120:123]
	v_mfma_f32_16x16x32_bf16 v[116:119], v[142:145], v[174:177], v[116:119]
	v_mfma_f32_16x16x32_bf16 v[112:115], v[134:137], v[230:233], v[112:115]
	v_mfma_f32_16x16x32_bf16 v[108:111], v[142:145], v[230:233], v[108:111]
	v_mfma_f32_16x16x32_bf16 v[104:107], v[134:137], v[238:241], v[104:107]
	v_mfma_f32_16x16x32_bf16 v[4:7], v[142:145], v[238:241], v[4:7]
	v_mfma_f32_16x16x32_bf16 v[124:127], v[138:141], v[170:173], v[124:127]
	v_mfma_f32_16x16x32_bf16 v[0:3], v[146:149], v[170:173], v[0:3]
	v_mfma_f32_16x16x32_bf16 v[120:123], v[138:141], v[178:181], v[120:123]
	v_mfma_f32_16x16x32_bf16 v[116:119], v[146:149], v[178:181], v[116:119]
	v_mfma_f32_16x16x32_bf16 v[112:115], v[138:141], v[234:237], v[112:115]
	v_mfma_f32_16x16x32_bf16 v[108:111], v[146:149], v[234:237], v[108:111]
	v_mfma_f32_16x16x32_bf16 v[104:107], v[138:141], v[242:245], v[104:107]
	v_mfma_f32_16x16x32_bf16 v[4:7], v[146:149], v[242:245], v[4:7]
	s_setprio 0
	s_setprio 1
	v_mfma_f32_16x16x32_bf16 v[100:103], v[150:153], v[166:169], v[100:103]
	v_mfma_f32_16x16x32_bf16 v[96:99], v[158:161], v[166:169], v[96:99]
	v_mfma_f32_16x16x32_bf16 v[92:95], v[150:153], v[174:177], v[92:95]
	v_mfma_f32_16x16x32_bf16 v[88:91], v[158:161], v[174:177], v[88:91]
	v_mfma_f32_16x16x32_bf16 v[84:87], v[150:153], v[230:233], v[84:87]
	v_mfma_f32_16x16x32_bf16 v[80:83], v[158:161], v[230:233], v[80:83]
	v_mfma_f32_16x16x32_bf16 v[76:79], v[150:153], v[238:241], v[76:79]
	v_mfma_f32_16x16x32_bf16 v[72:75], v[158:161], v[238:241], v[72:75]
	v_mfma_f32_16x16x32_bf16 v[100:103], v[154:157], v[170:173], v[100:103]
	v_mfma_f32_16x16x32_bf16 v[96:99], v[162:165], v[170:173], v[96:99]
	v_mfma_f32_16x16x32_bf16 v[92:95], v[154:157], v[178:181], v[92:95]
	v_mfma_f32_16x16x32_bf16 v[88:91], v[162:165], v[178:181], v[88:91]
	v_mfma_f32_16x16x32_bf16 v[84:87], v[154:157], v[234:237], v[84:87]
	v_mfma_f32_16x16x32_bf16 v[80:83], v[162:165], v[234:237], v[80:83]
	v_mfma_f32_16x16x32_bf16 v[76:79], v[154:157], v[242:245], v[76:79]
	v_mfma_f32_16x16x32_bf16 v[72:75], v[162:165], v[242:245], v[72:75]
	s_setprio 0
	s_barrier
; #define PG8_STAGE(bufoff, gbase, voff) do { _Pragma("unroll") for (int _i = 0; _i < 2; ++_i) \
;         __builtin_amdgcn_global_load_lds((const unsigned*)((const char*)(gbase) + (voff)[_i]), (LAS unsigned*)(lds + (bufoff) + ldsw + _i * 8192), 16, 0, 0); } while (0)
; #define PG8_LDA(dst, b, h) do { _Pragma("unroll") for (int m = 0; m < 4; ++m) _Pragma("unroll") for (int k = 0; k < 2; ++k) dst[m][k] = *(const LAS bf16x8*)(lds + PG8_SA(b, h) + aoff + m * 2048 + k * 1024); } while (0)
; #define PG8_MMA(ai, bj, At, Bt) do { __builtin_amdgcn_s_setprio(1); _Pragma("unroll") for (int m = 0; m < 4; ++m) _Pragma("unroll") for (int n = 0; n < 2; ++n) _Pragma("unroll") for (int k = 0; k < 2; ++k) \
;         acc[ai][bj][m][n] = __builtin_amdgcn_mfma_f32_16x16x32_bf16(Bt[n][k], At[m][k], acc[ai][bj][m][n], 0, 0, 0); __builtin_amdgcn_s_setprio(0); } while (0)
; #define PG8_WAIT_V(n) asm volatile("s_waitcnt vmcnt(" #n ")" ::: "memory")
; #define PG8_WAIT_L(n) asm volatile("s_waitcnt lgkmcnt(" #n ")" ::: "memory")
; #define PG8_BAR __builtin_amdgcn_s_barrier()
; #define PG8_SCHED __builtin_amdgcn_sched_barrier(0)
;     ...
;             PG8_LDA(At, 1, 1); PG8_STAGE(PG8_SB(1, 0), b3, voffB); PG8_STAGE(PG8_SB(1, 1), b3 + hstepB, voffB); PG8_STAGE(PG8_SA(1, 0), a3, voffA);
;             PG8_WAIT_V(8); PG8_WAIT_L(0); PG8_BAR; PG8_MMA(1, 0, At, B0); PG8_MMA(1, 1, At, B1); PG8_BAR; PG8_SCHED;
;         }
;         if (wr == 0) PG8_BAR;
	s_add_i32 s8, s26, s11
	v_lshl_add_u64 v[212:213], v[212:213], 0, s[70:71]
	s_mov_b32 m0, s8
	ds_read_b128 v[166:169], v227 offset:49152
	ds_read_b128 v[170:173], v227 offset:50176
	ds_read_b128 v[174:177], v227 offset:51200
	ds_read_b128 v[178:181], v227 offset:52224
	ds_read_b128 v[230:233], v227 offset:53248
	ds_read_b128 v[234:237], v227 offset:54272
	ds_read_b128 v[238:241], v227 offset:55296
	ds_read_b128 v[242:245], v227 offset:56320
	global_load_lds_dwordx4 v[212:213], off
	v_lshl_add_u64 v[212:213], v[218:219], 0, s[70:71]
	s_add_i32 m0, s8, 0x2000
	s_add_i32 s8, s27, s11
	global_load_lds_dwordx4 v[212:213], off
	v_lshl_add_u64 v[212:213], v[246:247], 0, s[70:71]
	s_mov_b32 m0, s8
	v_lshl_add_u64 v[204:205], v[204:205], 0, s[70:71]
	global_load_lds_dwordx4 v[212:213], off
	s_add_i32 m0, s8, 0x2000
	s_nop 0
	global_load_lds_dwordx4 v[204:205], off
	v_lshl_add_u64 v[204:205], v[248:249], 0, s[70:71]
	s_mov_b32 m0, s65
	s_nop 0
	global_load_lds_dwordx4 v[204:205], off
	v_lshl_add_u64 v[204:205], v[250:251], 0, s[70:71]
	s_mov_b32 m0, s49
	s_nop 0
	global_load_lds_dwordx4 v[204:205], off
	s_waitcnt vmcnt(8)
	s_waitcnt lgkmcnt(0)
	s_waitcnt lgkmcnt(0)
	s_barrier
	s_setprio 1
	v_mfma_f32_16x16x32_bf16 v[68:71], v[134:137], v[166:169], v[68:71]
	v_mfma_f32_16x16x32_bf16 v[8:11], v[142:145], v[166:169], v[8:11]
	v_mfma_f32_16x16x32_bf16 v[64:67], v[134:137], v[174:177], v[64:67]
	v_mfma_f32_16x16x32_bf16 v[60:63], v[142:145], v[174:177], v[60:63]
	v_mfma_f32_16x16x32_bf16 v[56:59], v[134:137], v[230:233], v[56:59]
	v_mfma_f32_16x16x32_bf16 v[52:55], v[142:145], v[230:233], v[52:55]
	v_mfma_f32_16x16x32_bf16 v[48:51], v[134:137], v[238:241], v[48:51]
	v_mfma_f32_16x16x32_bf16 v[12:15], v[142:145], v[238:241], v[12:15]
	v_mfma_f32_16x16x32_bf16 v[68:71], v[138:141], v[170:173], v[68:71]
	v_mfma_f32_16x16x32_bf16 v[8:11], v[146:149], v[170:173], v[8:11]
	v_mfma_f32_16x16x32_bf16 v[64:67], v[138:141], v[178:181], v[64:67]
	v_mfma_f32_16x16x32_bf16 v[60:63], v[146:149], v[178:181], v[60:63]
	v_mfma_f32_16x16x32_bf16 v[56:59], v[138:141], v[234:237], v[56:59]
	v_mfma_f32_16x16x32_bf16 v[52:55], v[146:149], v[234:237], v[52:55]
	v_mfma_f32_16x16x32_bf16 v[48:51], v[138:141], v[242:245], v[48:51]
	v_mfma_f32_16x16x32_bf16 v[12:15], v[146:149], v[242:245], v[12:15]
	s_setprio 0
	s_setprio 1
	v_mfma_f32_16x16x32_bf16 v[44:47], v[150:153], v[166:169], v[44:47]
	v_mfma_f32_16x16x32_bf16 v[40:43], v[158:161], v[166:169], v[40:43]
	v_mfma_f32_16x16x32_bf16 v[36:39], v[150:153], v[174:177], v[36:39]
	v_mfma_f32_16x16x32_bf16 v[32:35], v[158:161], v[174:177], v[32:35]
	v_mfma_f32_16x16x32_bf16 v[28:31], v[150:153], v[230:233], v[28:31]
	v_mfma_f32_16x16x32_bf16 v[24:27], v[158:161], v[230:233], v[24:27]
	v_mfma_f32_16x16x32_bf16 v[20:23], v[150:153], v[238:241], v[20:23]
	v_mfma_f32_16x16x32_bf16 v[16:19], v[158:161], v[238:241], v[16:19]
	v_mfma_f32_16x16x32_bf16 v[44:47], v[154:157], v[170:173], v[44:47]
	v_mfma_f32_16x16x32_bf16 v[40:43], v[162:165], v[170:173], v[40:43]
	v_mfma_f32_16x16x32_bf16 v[36:39], v[154:157], v[178:181], v[36:39]
	v_mfma_f32_16x16x32_bf16 v[32:35], v[162:165], v[178:181], v[32:35]
	v_mfma_f32_16x16x32_bf16 v[28:31], v[154:157], v[234:237], v[28:31]
	v_mfma_f32_16x16x32_bf16 v[24:27], v[162:165], v[234:237], v[24:27]
	v_mfma_f32_16x16x32_bf16 v[20:23], v[154:157], v[242:245], v[20:23]
	v_mfma_f32_16x16x32_bf16 v[16:19], v[162:165], v[242:245], v[16:19]
	s_setprio 0
	s_barrier
	s_add_u32 s0, s0, 0x100
	s_addc_u32 s1, s1, 0
	v_lshl_add_u64 v[130:131], v[130:131], 0, s[94:95]
	v_lshl_add_u64 v[128:129], v[128:129], 0, s[94:95]
	s_cmp_ge_u32 s38, s52
	s_mov_b32 s8, s38
	s_cbranch_scc0 .LBB0_159
	v_readlane_b32 s0, v254, 50
	v_readlane_b32 s1, v254, 51
	s_and_b64 vcc, exec, s[0:1]
	s_movk_i32 s67, 0xfe
	s_cbranch_vccz .LBB0_162
	s_barrier

; #define PG8_STAGE(bufoff, gbase, voff) do { _Pragma("unroll") for (int _i = 0; _i < 2; ++_i) \
;         __builtin_amdgcn_global_load_lds((const unsigned*)((const char*)(gbase) + (voff)[_i]), (LAS unsigned*)(lds + (bufoff) + ldsw + _i * 8192), 16, 0, 0); } while (0)
; #define PG8_LDA(dst, b, h) do { _Pragma("unroll") for (int m = 0; m < 4; ++m) _Pragma("unroll") for (int k = 0; k < 2; ++k) dst[m][k] = *(const LAS bf16x8*)(lds + PG8_SA(b, h) + aoff + m * 2048 + k * 1024); } while (0)
; #define PG8_LDB(dst, b, h) do { _Pragma("unroll") for (int n = 0; n < 2; ++n) _Pragma("unroll") for (int k = 0; k < 2; ++k) dst[n][k] = *(const LAS bf16x8*)(lds + PG8_SB(b, h) + boff + n * 2048 + k * 1024); } while (0)
; #define PG8_MMA(ai, bj, At, Bt) do { __builtin_amdgcn_s_setprio(1); _Pragma("unroll") for (int m = 0; m < 4; ++m) _Pragma("unroll") for (int n = 0; n < 2; ++n) _Pragma("unroll") for (int k = 0; k < 2; ++k) \
;         acc[ai][bj][m][n] = __builtin_amdgcn_mfma_f32_16x16x32_bf16(Bt[n][k], At[m][k], acc[ai][bj][m][n], 0, 0, 0); __builtin_amdgcn_s_setprio(0); } while (0)
; #define PG8_WAIT_V(n) asm volatile("s_waitcnt vmcnt(" #n ")" ::: "memory")
; #define PG8_WAIT_L(n) asm volatile("s_waitcnt lgkmcnt(" #n ")" ::: "memory")
; #define PG8_BAR __builtin_amdgcn_s_barrier()
; #define PG8_SCHED __builtin_amdgcn_sched_barrier(0)
;     ...
;             const bool last = (t == nt - 2);
;             const char* a1 = cA + (size_t)(t + 1) * kstep;
;             const char* a2 = last ? nA : cA + (size_t)(t + 2) * kstep; const char* b2 = last ? nB : cB + (size_t)(t + 2) * kstep;
;             const char* a3 = a2 + kstep; const char* b3 = b2 + kstep;
;             PG8_LDB(B0, 0, 0); PG8_LDB(B1, 0, 1); PG8_SCHED; PG8_LDA(At, 0, 0); PG8_STAGE(PG8_SA(1, 1), a1 + hstepA, voffA);
;             PG8_WAIT_V(8); PG8_WAIT_L(0); PG8_BAR; PG8_MMA(0, 0, At, B0); PG8_MMA(0, 1, At, B1); PG8_BAR; PG8_SCHED;
;             PG8_LDA(At, 0, 1); PG8_STAGE(PG8_SB(0, 0), b2, voffB); PG8_STAGE(PG8_SB(0, 1), b2 + hstepB, voffB); PG8_STAGE(PG8_SA(0, 0), a2, voffA);
;             PG8_WAIT_V(8); PG8_WAIT_L(0); PG8_BAR; PG8_MMA(1, 0, At, B0); PG8_MMA(1, 1, At, B1); PG8_BAR; PG8_SCHED;
.LBB0_318:
	s_add_i32 s57, s38, 2
	s_add_u32 s19, s2, s0
	s_addc_u32 s27, s3, s1
	s_add_i32 s58, 0, 0x10000
	s_cmp_eq_u32 s51, s38
	s_cselect_b32 s39, s13, s27
	s_cselect_b32 s38, s56, s19
	s_cselect_b64 vcc, -1, 0
	s_add_i32 s19, 0, 0x14000
	v_lshl_add_u64 v[150:151], v[160:161], 0, s[0:1]
	v_add_u32_e32 v146, s58, v181
	s_waitcnt lgkmcnt(0)
	v_add_u32_e32 v178, s19, v181
	ds_read_b128 v[134:137], v146
	ds_read_b128 v[138:141], v146 offset:1024
	ds_read_b128 v[142:145], v146 offset:2048
	ds_read_b128 v[146:149], v146 offset:3072
	v_cndmask_b32_e32 v159, v151, v132, vcc
	v_cndmask_b32_e32 v158, v150, v133, vcc
	ds_read_b128 v[150:153], v178
	ds_read_b128 v[154:157], v178 offset:1024
	ds_read_b128 v[174:177], v178 offset:2048
	ds_read_b128 v[190:193], v178 offset:3072
	v_lshl_add_u64 v[178:179], s[2:3], 0, v[130:131]
	s_add_i32 m0, s11, 0xc000
	ds_read_b128 v[194:197], v188
	ds_read_b128 v[198:201], v188 offset:1024
	ds_read_b128 v[202:205], v188 offset:2048
	ds_read_b128 v[224:227], v188 offset:3072
	ds_read_b128 v[228:231], v188 offset:4096
	ds_read_b128 v[232:235], v188 offset:5120
	ds_read_b128 v[236:239], v188 offset:6144
	ds_read_b128 v[240:243], v188 offset:7168
	global_load_lds_dwordx4 v[178:179], off
	v_lshl_add_u64 v[178:179], s[2:3], 0, v[128:129]
	s_add_i32 m0, s11, 0xe000
	s_nop 0
	global_load_lds_dwordx4 v[178:179], off
	s_waitcnt vmcnt(8)
	s_waitcnt lgkmcnt(0)
	s_waitcnt lgkmcnt(0)
	s_barrier
	s_setprio 1
	v_mfma_f32_16x16x32_bf16 v[124:127], v[134:137], v[194:197], v[124:127]
	v_mfma_f32_16x16x32_bf16 v[120:123], v[142:145], v[194:197], v[120:123]
	v_mfma_f32_16x16x32_bf16 v[116:119], v[134:137], v[202:205], v[116:119]
	v_mfma_f32_16x16x32_bf16 v[112:115], v[142:145], v[202:205], v[112:115]
	v_mfma_f32_16x16x32_bf16 v[108:111], v[134:137], v[228:231], v[108:111]
	v_mfma_f32_16x16x32_bf16 v[104:107], v[142:145], v[228:231], v[104:107]
	v_mfma_f32_16x16x32_bf16 v[100:103], v[134:137], v[236:239], v[100:103]
	v_mfma_f32_16x16x32_bf16 v[96:99], v[142:145], v[236:239], v[96:99]
	v_mfma_f32_16x16x32_bf16 v[124:127], v[138:141], v[198:201], v[124:127]
	v_mfma_f32_16x16x32_bf16 v[120:123], v[146:149], v[198:201], v[120:123]
	v_mfma_f32_16x16x32_bf16 v[116:119], v[138:141], v[224:227], v[116:119]
	v_mfma_f32_16x16x32_bf16 v[112:115], v[146:149], v[224:227], v[112:115]
	v_mfma_f32_16x16x32_bf16 v[108:111], v[138:141], v[232:235], v[108:111]
	v_mfma_f32_16x16x32_bf16 v[104:107], v[146:149], v[232:235], v[104:107]
	v_mfma_f32_16x16x32_bf16 v[100:103], v[138:141], v[240:243], v[100:103]
	v_mfma_f32_16x16x32_bf16 v[96:99], v[146:149], v[240:243], v[96:99]
	s_setprio 0
	s_setprio 1
	v_mfma_f32_16x16x32_bf16 v[92:95], v[150:153], v[194:197], v[92:95]
	v_mfma_f32_16x16x32_bf16 v[88:91], v[174:177], v[194:197], v[88:91]
	v_mfma_f32_16x16x32_bf16 v[84:87], v[150:153], v[202:205], v[84:87]
	v_mfma_f32_16x16x32_bf16 v[80:83], v[174:177], v[202:205], v[80:83]
	v_mfma_f32_16x16x32_bf16 v[76:79], v[150:153], v[228:231], v[76:79]
	v_mfma_f32_16x16x32_bf16 v[72:75], v[174:177], v[228:231], v[72:75]
	v_mfma_f32_16x16x32_bf16 v[68:71], v[150:153], v[236:239], v[68:71]
	v_mfma_f32_16x16x32_bf16 v[64:67], v[174:177], v[236:239], v[64:67]
	v_mfma_f32_16x16x32_bf16 v[92:95], v[154:157], v[198:201], v[92:95]
	v_mfma_f32_16x16x32_bf16 v[88:91], v[190:193], v[198:201], v[88:91]
	v_mfma_f32_16x16x32_bf16 v[84:87], v[154:157], v[224:227], v[84:87]
	v_mfma_f32_16x16x32_bf16 v[80:83], v[190:193], v[224:227], v[80:83]
	v_mfma_f32_16x16x32_bf16 v[76:79], v[154:157], v[232:235], v[76:79]
	v_mfma_f32_16x16x32_bf16 v[72:75], v[190:193], v[232:235], v[72:75]
	v_mfma_f32_16x16x32_bf16 v[68:71], v[154:157], v[240:243], v[68:71]
	v_mfma_f32_16x16x32_bf16 v[64:67], v[190:193], v[240:243], v[64:67]
	s_setprio 0
	s_barrier
	s_add_i32 s27, s58, s10
	v_lshl_add_u64 v[178:179], v[158:159], 0, v[164:165]
	s_mov_b32 m0, s27
	ds_read_b128 v[194:197], v188 offset:16384
	ds_read_b128 v[198:201], v188 offset:17408
	ds_read_b128 v[202:205], v188 offset:18432
	ds_read_b128 v[224:227], v188 offset:19456
	ds_read_b128 v[228:231], v188 offset:20480
	ds_read_b128 v[232:235], v188 offset:21504
	ds_read_b128 v[236:239], v188 offset:22528
	ds_read_b128 v[240:243], v188 offset:23552
	global_load_lds_dwordx4 v[178:179], off
	v_lshl_add_u64 v[212:213], v[158:159], 0, v[168:169]
	s_add_i32 m0, s27, 0x2000
	v_lshl_add_u64 v[158:159], v[158:159], 0, s[96:97]
	s_add_i32 s19, s19, s10
	global_load_lds_dwordx4 v[212:213], off
	v_lshl_add_u64 v[218:219], v[158:159], 0, v[164:165]
	s_mov_b32 m0, s19
	v_lshl_add_u64 v[158:159], v[158:159], 0, v[168:169]
	global_load_lds_dwordx4 v[218:219], off
	s_add_i32 m0, s19, 0x2000
	v_lshl_add_u64 v[244:245], s[38:39], 0, v[162:163]
	global_load_lds_dwordx4 v[158:159], off
	s_mov_b32 m0, s11
	v_lshl_add_u64 v[246:247], s[38:39], 0, v[166:167]
	global_load_lds_dwordx4 v[244:245], off
	s_mov_b32 m0, s20
	s_nop 0
	global_load_lds_dwordx4 v[246:247], off
	s_waitcnt vmcnt(8)
	s_waitcnt lgkmcnt(0)
	s_waitcnt lgkmcnt(0)
	s_barrier
; #define PG8_STAGE(bufoff, gbase, voff) do { _Pragma("unroll") for (int _i = 0; _i < 2; ++_i) \
;         __builtin_amdgcn_global_load_lds((const unsigned*)((const char*)(gbase) + (voff)[_i]), (LAS unsigned*)(lds + (bufoff) + ldsw + _i * 8192), 16, 0, 0); } while (0)
; #define PG8_LDA(dst, b, h) do { _Pragma("unroll") for (int m = 0; m < 4; ++m) _Pragma("unroll") for (int k = 0; k < 2; ++k) dst[m][k] = *(const LAS bf16x8*)(lds + PG8_SA(b, h) + aoff + m * 2048 + k * 1024); } while (0)
; #define PG8_LDB(dst, b, h) do { _Pragma("unroll") for (int n = 0; n < 2; ++n) _Pragma("unroll") for (int k = 0; k < 2; ++k) dst[n][k] = *(const LAS bf16x8*)(lds + PG8_SB(b, h) + boff + n * 2048 + k * 1024); } while (0)
; #define PG8_MMA(ai, bj, At, Bt) do { __builtin_amdgcn_s_setprio(1); _Pragma("unroll") for (int m = 0; m < 4; ++m) _Pragma("unroll") for (int n = 0; n < 2; ++n) _Pragma("unroll") for (int k = 0; k < 2; ++k) \
;         acc[ai][bj][m][n] = __builtin_amdgcn_mfma_f32_16x16x32_bf16(Bt[n][k], At[m][k], acc[ai][bj][m][n], 0, 0, 0); __builtin_amdgcn_s_setprio(0); } while (0)
; #define PG8_WAIT_V(n) asm volatile("s_waitcnt vmcnt(" #n ")" ::: "memory")
; #define PG8_WAIT_L(n) asm volatile("s_waitcnt lgkmcnt(" #n ")" ::: "memory")
; #define PG8_BAR __builtin_amdgcn_s_barrier()
; #define PG8_SCHED __builtin_amdgcn_sched_barrier(0)
;     ...
;             PG8_WAIT_V(8); PG8_WAIT_L(0); PG8_BAR; PG8_MMA(1, 0, At, B0); PG8_MMA(1, 1, At, B1); PG8_BAR; PG8_SCHED;
;             PG8_LDB(B0, 1, 0); PG8_LDB(B1, 1, 1); PG8_SCHED; PG8_LDA(At, 1, 0); PG8_STAGE(PG8_SA(0, 1), a2 + hstepA, voffA);
;             PG8_WAIT_V(8); PG8_WAIT_L(0); PG8_BAR; PG8_MMA(0, 0, At, B0); PG8_MMA(0, 1, At, B1); PG8_BAR; PG8_SCHED;
	s_setprio 1
	v_mfma_f32_16x16x32_bf16 v[60:63], v[134:137], v[194:197], v[60:63]
	v_mfma_f32_16x16x32_bf16 v[56:59], v[142:145], v[194:197], v[56:59]
	v_mfma_f32_16x16x32_bf16 v[52:55], v[134:137], v[202:205], v[52:55]
	v_mfma_f32_16x16x32_bf16 v[48:51], v[142:145], v[202:205], v[48:51]
	v_mfma_f32_16x16x32_bf16 v[44:47], v[134:137], v[228:231], v[44:47]
	v_mfma_f32_16x16x32_bf16 v[40:43], v[142:145], v[228:231], v[40:43]
	v_mfma_f32_16x16x32_bf16 v[36:39], v[134:137], v[236:239], v[36:39]
	v_mfma_f32_16x16x32_bf16 v[32:35], v[142:145], v[236:239], v[32:35]
	v_mfma_f32_16x16x32_bf16 v[60:63], v[138:141], v[198:201], v[60:63]
	v_mfma_f32_16x16x32_bf16 v[56:59], v[146:149], v[198:201], v[56:59]
	v_mfma_f32_16x16x32_bf16 v[52:55], v[138:141], v[224:227], v[52:55]
	v_mfma_f32_16x16x32_bf16 v[48:51], v[146:149], v[224:227], v[48:51]
	v_mfma_f32_16x16x32_bf16 v[44:47], v[138:141], v[232:235], v[44:47]
	v_mfma_f32_16x16x32_bf16 v[40:43], v[146:149], v[232:235], v[40:43]
	v_mfma_f32_16x16x32_bf16 v[36:39], v[138:141], v[240:243], v[36:39]
	v_mfma_f32_16x16x32_bf16 v[32:35], v[146:149], v[240:243], v[32:35]
	s_setprio 0
	s_setprio 1
	v_mfma_f32_16x16x32_bf16 v[28:31], v[150:153], v[194:197], v[28:31]
	v_mfma_f32_16x16x32_bf16 v[24:27], v[174:177], v[194:197], v[24:27]
	v_mfma_f32_16x16x32_bf16 v[20:23], v[150:153], v[202:205], v[20:23]
	v_mfma_f32_16x16x32_bf16 v[16:19], v[174:177], v[202:205], v[16:19]
	v_mfma_f32_16x16x32_bf16 v[12:15], v[150:153], v[228:231], v[12:15]
	v_mfma_f32_16x16x32_bf16 v[8:11], v[174:177], v[228:231], v[8:11]
	v_mfma_f32_16x16x32_bf16 v[4:7], v[150:153], v[236:239], v[4:7]
	v_mfma_f32_16x16x32_bf16 v[0:3], v[174:177], v[236:239], v[0:3]
	v_mfma_f32_16x16x32_bf16 v[28:31], v[154:157], v[198:201], v[28:31]
	v_mfma_f32_16x16x32_bf16 v[24:27], v[190:193], v[198:201], v[24:27]
	v_mfma_f32_16x16x32_bf16 v[20:23], v[154:157], v[224:227], v[20:23]
	v_mfma_f32_16x16x32_bf16 v[16:19], v[190:193], v[224:227], v[16:19]
	v_mfma_f32_16x16x32_bf16 v[12:15], v[154:157], v[232:235], v[12:15]
	v_mfma_f32_16x16x32_bf16 v[8:11], v[190:193], v[232:235], v[8:11]
	v_mfma_f32_16x16x32_bf16 v[4:7], v[154:157], v[240:243], v[4:7]
	v_mfma_f32_16x16x32_bf16 v[0:3], v[190:193], v[240:243], v[0:3]
	s_setprio 0
	s_barrier
	s_add_i32 s19, 0, 0x18000
	s_add_i32 s27, 0, 0x1c000
	v_add_u32_e32 v146, s19, v181
	v_add_u32_e32 v182, s27, v181
	ds_read_b128 v[134:137], v146
	ds_read_b128 v[138:141], v146 offset:1024
	ds_read_b128 v[142:145], v146 offset:2048
	ds_read_b128 v[146:149], v146 offset:3072
	ds_read_b128 v[150:153], v182
	ds_read_b128 v[154:157], v182 offset:1024
	ds_read_b128 v[174:177], v182 offset:2048
	ds_read_b128 v[190:193], v182 offset:3072
	s_add_u32 s38, s38, s96
	s_addc_u32 s39, s39, 0
	s_mov_b32 m0, s48
	v_lshl_add_u64 v[248:249], s[38:39], 0, v[162:163]
	ds_read_b128 v[194:197], v188 offset:32768
	ds_read_b128 v[198:201], v188 offset:33792
	ds_read_b128 v[202:205], v188 offset:34816
	ds_read_b128 v[224:227], v188 offset:35840
	ds_read_b128 v[228:231], v188 offset:36864
	ds_read_b128 v[232:235], v188 offset:37888
	ds_read_b128 v[236:239], v188 offset:38912
	ds_read_b128 v[240:243], v188 offset:39936
	global_load_lds_dwordx4 v[248:249], off
	v_lshl_add_u64 v[248:249], s[38:39], 0, v[166:167]
	s_mov_b32 m0, s49
	s_nop 0
	global_load_lds_dwordx4 v[248:249], off
	s_waitcnt vmcnt(8)
	s_waitcnt lgkmcnt(0)
	s_waitcnt lgkmcnt(0)
	s_barrier
	s_setprio 1
	v_mfma_f32_16x16x32_bf16 v[124:127], v[134:137], v[194:197], v[124:127]
	v_mfma_f32_16x16x32_bf16 v[120:123], v[142:145], v[194:197], v[120:123]
	v_mfma_f32_16x16x32_bf16 v[116:119], v[134:137], v[202:205], v[116:119]
	v_mfma_f32_16x16x32_bf16 v[112:115], v[142:145], v[202:205], v[112:115]
	v_mfma_f32_16x16x32_bf16 v[108:111], v[134:137], v[228:231], v[108:111]
	v_mfma_f32_16x16x32_bf16 v[104:107], v[142:145], v[228:231], v[104:107]
	v_mfma_f32_16x16x32_bf16 v[100:103], v[134:137], v[236:239], v[100:103]
	v_mfma_f32_16x16x32_bf16 v[96:99], v[142:145], v[236:239], v[96:99]
	v_mfma_f32_16x16x32_bf16 v[124:127], v[138:141], v[198:201], v[124:127]
	v_mfma_f32_16x16x32_bf16 v[120:123], v[146:149], v[198:201], v[120:123]
	v_mfma_f32_16x16x32_bf16 v[116:119], v[138:141], v[224:227], v[116:119]
	v_mfma_f32_16x16x32_bf16 v[112:115], v[146:149], v[224:227], v[112:115]
	v_mfma_f32_16x16x32_bf16 v[108:111], v[138:141], v[232:235], v[108:111]
	v_mfma_f32_16x16x32_bf16 v[104:107], v[146:149], v[232:235], v[104:107]
	v_mfma_f32_16x16x32_bf16 v[100:103], v[138:141], v[240:243], v[100:103]
	v_mfma_f32_16x16x32_bf16 v[96:99], v[146:149], v[240:243], v[96:99]
	s_setprio 0
	s_setprio 1
	v_mfma_f32_16x16x32_bf16 v[92:95], v[150:153], v[194:197], v[92:95]
	v_mfma_f32_16x16x32_bf16 v[88:91], v[174:177], v[194:197], v[88:91]
	v_mfma_f32_16x16x32_bf16 v[84:87], v[150:153], v[202:205], v[84:87]
	v_mfma_f32_16x16x32_bf16 v[80:83], v[174:177], v[202:205], v[80:83]
	v_mfma_f32_16x16x32_bf16 v[76:79], v[150:153], v[228:231], v[76:79]
	v_mfma_f32_16x16x32_bf16 v[72:75], v[174:177], v[228:231], v[72:75]
	v_mfma_f32_16x16x32_bf16 v[68:71], v[150:153], v[236:239], v[68:71]
	v_mfma_f32_16x16x32_bf16 v[64:67], v[174:177], v[236:239], v[64:67]
	v_mfma_f32_16x16x32_bf16 v[92:95], v[154:157], v[198:201], v[92:95]
	v_mfma_f32_16x16x32_bf16 v[88:91], v[190:193], v[198:201], v[88:91]
	v_mfma_f32_16x16x32_bf16 v[84:87], v[154:157], v[224:227], v[84:87]
	v_mfma_f32_16x16x32_bf16 v[80:83], v[190:193], v[224:227], v[80:83]
	v_mfma_f32_16x16x32_bf16 v[76:79], v[154:157], v[232:235], v[76:79]
	v_mfma_f32_16x16x32_bf16 v[72:75], v[190:193], v[232:235], v[72:75]
	v_mfma_f32_16x16x32_bf16 v[68:71], v[154:157], v[240:243], v[68:71]
	v_mfma_f32_16x16x32_bf16 v[64:67], v[190:193], v[240:243], v[64:67]
	s_setprio 0
	s_barrier
; #define PG8_STAGE(bufoff, gbase, voff) do { _Pragma("unroll") for (int _i = 0; _i < 2; ++_i) \
;         __builtin_amdgcn_global_load_lds((const unsigned*)((const char*)(gbase) + (voff)[_i]), (LAS unsigned*)(lds + (bufoff) + ldsw + _i * 8192), 16, 0, 0); } while (0)
; #define PG8_LDA(dst, b, h) do { _Pragma("unroll") for (int m = 0; m < 4; ++m) _Pragma("unroll") for (int k = 0; k < 2; ++k) dst[m][k] = *(const LAS bf16x8*)(lds + PG8_SA(b, h) + aoff + m * 2048 + k * 1024); } while (0)
; #define PG8_MMA(ai, bj, At, Bt) do { __builtin_amdgcn_s_setprio(1); _Pragma("unroll") for (int m = 0; m < 4; ++m) _Pragma("unroll") for (int n = 0; n < 2; ++n) _Pragma("unroll") for (int k = 0; k < 2; ++k) \
;         acc[ai][bj][m][n] = __builtin_amdgcn_mfma_f32_16x16x32_bf16(Bt[n][k], At[m][k], acc[ai][bj][m][n], 0, 0, 0); __builtin_amdgcn_s_setprio(0); } while (0)
; #define PG8_WAIT_V(n) asm volatile("s_waitcnt vmcnt(" #n ")" ::: "memory")
; #define PG8_WAIT_L(n) asm volatile("s_waitcnt lgkmcnt(" #n ")" ::: "memory")
; #define PG8_BAR __builtin_amdgcn_s_barrier()
; #define PG8_SCHED __builtin_amdgcn_sched_barrier(0)
;     ...
;             PG8_LDA(At, 1, 1); PG8_STAGE(PG8_SB(1, 0), b3, voffB); PG8_STAGE(PG8_SB(1, 1), b3 + hstepB, voffB); PG8_STAGE(PG8_SA(1, 0), a3, voffA);
;             PG8_WAIT_V(8); PG8_WAIT_L(0); PG8_BAR; PG8_MMA(1, 0, At, B0); PG8_MMA(1, 1, At, B1); PG8_BAR; PG8_SCHED;
;         }
;         if (wr == 0) PG8_BAR;
	s_add_i32 s19, s19, s10
	v_lshl_add_u64 v[178:179], v[178:179], 0, s[70:71]
	s_mov_b32 m0, s19
	ds_read_b128 v[194:197], v188 offset:49152
	ds_read_b128 v[198:201], v188 offset:50176
	ds_read_b128 v[202:205], v188 offset:51200
	ds_read_b128 v[224:227], v188 offset:52224
	ds_read_b128 v[228:231], v188 offset:53248
	ds_read_b128 v[232:235], v188 offset:54272
	ds_read_b128 v[236:239], v188 offset:55296
	ds_read_b128 v[240:243], v188 offset:56320
	global_load_lds_dwordx4 v[178:179], off
	v_lshl_add_u64 v[178:179], v[212:213], 0, s[70:71]
	s_add_i32 m0, s19, 0x2000
	s_add_i32 s19, s27, s10
	global_load_lds_dwordx4 v[178:179], off
	v_lshl_add_u64 v[178:179], v[218:219], 0, s[70:71]
	s_mov_b32 m0, s19
	v_lshl_add_u64 v[158:159], v[158:159], 0, s[70:71]
	global_load_lds_dwordx4 v[178:179], off
	s_add_i32 m0, s19, 0x2000
	s_nop 0
	global_load_lds_dwordx4 v[158:159], off
	v_lshl_add_u64 v[158:159], v[244:245], 0, s[70:71]
	s_mov_b32 m0, s62
	s_nop 0
	global_load_lds_dwordx4 v[158:159], off
	v_lshl_add_u64 v[158:159], v[246:247], 0, s[70:71]
	s_mov_b32 m0, s63
	s_nop 0
	global_load_lds_dwordx4 v[158:159], off
	s_waitcnt vmcnt(8)
	s_waitcnt lgkmcnt(0)
	s_waitcnt lgkmcnt(0)
	s_barrier
	s_setprio 1
	v_mfma_f32_16x16x32_bf16 v[60:63], v[134:137], v[194:197], v[60:63]
	v_mfma_f32_16x16x32_bf16 v[56:59], v[142:145], v[194:197], v[56:59]
	v_mfma_f32_16x16x32_bf16 v[52:55], v[134:137], v[202:205], v[52:55]
	v_mfma_f32_16x16x32_bf16 v[48:51], v[142:145], v[202:205], v[48:51]
	v_mfma_f32_16x16x32_bf16 v[44:47], v[134:137], v[228:231], v[44:47]
	v_mfma_f32_16x16x32_bf16 v[40:43], v[142:145], v[228:231], v[40:43]
	v_mfma_f32_16x16x32_bf16 v[36:39], v[134:137], v[236:239], v[36:39]
	v_mfma_f32_16x16x32_bf16 v[32:35], v[142:145], v[236:239], v[32:35]
	v_mfma_f32_16x16x32_bf16 v[60:63], v[138:141], v[198:201], v[60:63]
	v_mfma_f32_16x16x32_bf16 v[56:59], v[146:149], v[198:201], v[56:59]
	v_mfma_f32_16x16x32_bf16 v[52:55], v[138:141], v[224:227], v[52:55]
	v_mfma_f32_16x16x32_bf16 v[48:51], v[146:149], v[224:227], v[48:51]
	v_mfma_f32_16x16x32_bf16 v[44:47], v[138:141], v[232:235], v[44:47]
	v_mfma_f32_16x16x32_bf16 v[40:43], v[146:149], v[232:235], v[40:43]
	v_mfma_f32_16x16x32_bf16 v[36:39], v[138:141], v[240:243], v[36:39]
	v_mfma_f32_16x16x32_bf16 v[32:35], v[146:149], v[240:243], v[32:35]
	s_setprio 0
	s_setprio 1
	v_mfma_f32_16x16x32_bf16 v[28:31], v[150:153], v[194:197], v[28:31]
	v_mfma_f32_16x16x32_bf16 v[24:27], v[174:177], v[194:197], v[24:27]
	v_mfma_f32_16x16x32_bf16 v[20:23], v[150:153], v[202:205], v[20:23]
	v_mfma_f32_16x16x32_bf16 v[16:19], v[174:177], v[202:205], v[16:19]
	v_mfma_f32_16x16x32_bf16 v[12:15], v[150:153], v[228:231], v[12:15]
	v_mfma_f32_16x16x32_bf16 v[8:11], v[174:177], v[228:231], v[8:11]
	v_mfma_f32_16x16x32_bf16 v[4:7], v[150:153], v[236:239], v[4:7]
	v_mfma_f32_16x16x32_bf16 v[0:3], v[174:177], v[236:239], v[0:3]
	v_mfma_f32_16x16x32_bf16 v[28:31], v[154:157], v[198:201], v[28:31]
	v_mfma_f32_16x16x32_bf16 v[24:27], v[190:193], v[198:201], v[24:27]
	v_mfma_f32_16x16x32_bf16 v[20:23], v[154:157], v[224:227], v[20:23]
	v_mfma_f32_16x16x32_bf16 v[16:19], v[190:193], v[224:227], v[16:19]
	v_mfma_f32_16x16x32_bf16 v[12:15], v[154:157], v[232:235], v[12:15]
	v_mfma_f32_16x16x32_bf16 v[8:11], v[190:193], v[232:235], v[8:11]
	v_mfma_f32_16x16x32_bf16 v[4:7], v[154:157], v[240:243], v[4:7]
	v_mfma_f32_16x16x32_bf16 v[0:3], v[190:193], v[240:243], v[0:3]
	s_setprio 0
	s_barrier
	s_add_u32 s0, s0, 0x100
	s_addc_u32 s1, s1, 0
	v_lshl_add_u64 v[130:131], v[130:131], 0, s[94:95]
	v_lshl_add_u64 v[128:129], v[128:129], 0, s[94:95]
	s_cmp_ge_u32 s57, s16
	s_mov_b32 s38, s57
	s_cbranch_scc0 .LBB0_318
	v_readlane_b32 s0, v254, 50
	v_readlane_b32 s1, v254, 51
	s_and_b64 vcc, exec, s[0:1]
	s_mov_b32 s68, 0x134000
	s_mov_b32 s69, 0x160000
	s_cbranch_vccz .LBB0_321
	s_barrier

; #define PG8_STAGE(bufoff, gbase, voff) do { _Pragma("unroll") for (int _i = 0; _i < 2; ++_i) \
;         __builtin_amdgcn_global_load_lds((const unsigned*)((const char*)(gbase) + (voff)[_i]), (LAS unsigned*)(lds + (bufoff) + ldsw + _i * 8192), 16, 0, 0); } while (0)
; #define PG8_LDA(dst, b, h) do { _Pragma("unroll") for (int m = 0; m < 4; ++m) _Pragma("unroll") for (int k = 0; k < 2; ++k) dst[m][k] = *(const LAS bf16x8*)(lds + PG8_SA(b, h) + aoff + m * 2048 + k * 1024); } while (0)
; #define PG8_LDB(dst, b, h) do { _Pragma("unroll") for (int n = 0; n < 2; ++n) _Pragma("unroll") for (int k = 0; k < 2; ++k) dst[n][k] = *(const LAS bf16x8*)(lds + PG8_SB(b, h) + boff + n * 2048 + k * 1024); } while (0)
; #define PG8_MMA(ai, bj, At, Bt) do { __builtin_amdgcn_s_setprio(1); _Pragma("unroll") for (int m = 0; m < 4; ++m) _Pragma("unroll") for (int n = 0; n < 2; ++n) _Pragma("unroll") for (int k = 0; k < 2; ++k) \
;         acc[ai][bj][m][n] = __builtin_amdgcn_mfma_f32_16x16x32_bf16(Bt[n][k], At[m][k], acc[ai][bj][m][n], 0, 0, 0); __builtin_amdgcn_s_setprio(0); } while (0)
; #define PG8_WAIT_V(n) asm volatile("s_waitcnt vmcnt(" #n ")" ::: "memory")
; #define PG8_WAIT_L(n) asm volatile("s_waitcnt lgkmcnt(" #n ")" ::: "memory")
; #define PG8_BAR __builtin_amdgcn_s_barrier()
; #define PG8_SCHED __builtin_amdgcn_sched_barrier(0)
;     ...
;             const bool last = (t == nt - 2);
;             const char* a1 = cA + (size_t)(t + 1) * kstep;
;             const char* a2 = last ? nA : cA + (size_t)(t + 2) * kstep; const char* b2 = last ? nB : cB + (size_t)(t + 2) * kstep;
;             const char* a3 = a2 + kstep; const char* b3 = b2 + kstep;
;             PG8_LDB(B0, 0, 0); PG8_LDB(B1, 0, 1); PG8_SCHED; PG8_LDA(At, 0, 0); PG8_STAGE(PG8_SA(1, 1), a1 + hstepA, voffA);
;             PG8_WAIT_V(8); PG8_WAIT_L(0); PG8_BAR; PG8_MMA(0, 0, At, B0); PG8_MMA(0, 1, At, B1); PG8_BAR; PG8_SCHED;
;             PG8_LDA(At, 0, 1); PG8_STAGE(PG8_SB(0, 0), b2, voffB); PG8_STAGE(PG8_SB(0, 1), b2 + hstepB, voffB); PG8_STAGE(PG8_SA(0, 0), a2, voffA);
;             PG8_WAIT_V(8); PG8_WAIT_L(0); PG8_BAR; PG8_MMA(1, 0, At, B0); PG8_MMA(1, 1, At, B1); PG8_BAR; PG8_SCHED;
.LBB0_416:
	s_add_i32 s8, s2, 2
	s_add_u32 s9, s52, s0
	s_addc_u32 s3, s53, s1
	s_add_i32 s26, 0, 0x10000
	s_cmp_eq_u32 s65, s2
	s_cselect_b32 s3, s6, s3
	s_cselect_b32 s2, s7, s9
	v_add_u32_e32 v153, s26, v148
	s_cselect_b64 vcc, -1, 0
	s_add_i32 s9, 0, 0x14000
	v_lshl_add_u64 v[170:171], v[128:129], 0, s[0:1]
	ds_read_b128 v[154:157], v153
	ds_read_b128 v[158:161], v153 offset:1024
	ds_read_b128 v[162:165], v153 offset:2048
	ds_read_b128 v[166:169], v153 offset:3072
	v_add_u32_e32 v153, s9, v148
	v_cndmask_b32_e32 v205, v171, v151, vcc
	v_cndmask_b32_e32 v204, v170, v152, vcc
	ds_read_b128 v[170:173], v153
	ds_read_b128 v[174:177], v153 offset:1024
	ds_read_b128 v[178:181], v153 offset:2048
	ds_read_b128 v[188:191], v153 offset:3072
	v_lshl_add_u64 v[244:245], s[52:53], 0, v[146:147]
	s_add_i32 m0, s41, 0xc000
	ds_read_b128 v[192:195], v149
	ds_read_b128 v[196:199], v149 offset:1024
	ds_read_b128 v[200:203], v149 offset:2048
	ds_read_b128 v[224:227], v149 offset:3072
	ds_read_b128 v[228:231], v149 offset:4096
	ds_read_b128 v[232:235], v149 offset:5120
	ds_read_b128 v[236:239], v149 offset:6144
	ds_read_b128 v[240:243], v149 offset:7168
	global_load_lds_dwordx4 v[244:245], off
	v_lshl_add_u64 v[244:245], s[52:53], 0, v[144:145]
	s_add_i32 m0, s41, 0xe000
	s_nop 0
	global_load_lds_dwordx4 v[244:245], off
	s_waitcnt vmcnt(8)
	s_waitcnt lgkmcnt(0)
	s_waitcnt lgkmcnt(0)
	s_barrier
	s_setprio 1
	v_mfma_f32_16x16x32_bf16 v[124:127], v[154:157], v[192:195], v[124:127]
	v_mfma_f32_16x16x32_bf16 v[120:123], v[162:165], v[192:195], v[120:123]
	v_mfma_f32_16x16x32_bf16 v[116:119], v[154:157], v[200:203], v[116:119]
	v_mfma_f32_16x16x32_bf16 v[112:115], v[162:165], v[200:203], v[112:115]
	v_mfma_f32_16x16x32_bf16 v[108:111], v[154:157], v[228:231], v[108:111]
	v_mfma_f32_16x16x32_bf16 v[104:107], v[162:165], v[228:231], v[104:107]
	v_mfma_f32_16x16x32_bf16 v[100:103], v[154:157], v[236:239], v[100:103]
	v_mfma_f32_16x16x32_bf16 v[96:99], v[162:165], v[236:239], v[96:99]
	v_mfma_f32_16x16x32_bf16 v[124:127], v[158:161], v[196:199], v[124:127]
	v_mfma_f32_16x16x32_bf16 v[120:123], v[166:169], v[196:199], v[120:123]
	v_mfma_f32_16x16x32_bf16 v[116:119], v[158:161], v[224:227], v[116:119]
	v_mfma_f32_16x16x32_bf16 v[112:115], v[166:169], v[224:227], v[112:115]
	v_mfma_f32_16x16x32_bf16 v[108:111], v[158:161], v[232:235], v[108:111]
	v_mfma_f32_16x16x32_bf16 v[104:107], v[166:169], v[232:235], v[104:107]
	v_mfma_f32_16x16x32_bf16 v[100:103], v[158:161], v[240:243], v[100:103]
	v_mfma_f32_16x16x32_bf16 v[96:99], v[166:169], v[240:243], v[96:99]
	s_setprio 0
	s_setprio 1
	v_mfma_f32_16x16x32_bf16 v[92:95], v[170:173], v[192:195], v[92:95]
	v_mfma_f32_16x16x32_bf16 v[88:91], v[178:181], v[192:195], v[88:91]
	v_mfma_f32_16x16x32_bf16 v[84:87], v[170:173], v[200:203], v[84:87]
	v_mfma_f32_16x16x32_bf16 v[80:83], v[178:181], v[200:203], v[80:83]
	v_mfma_f32_16x16x32_bf16 v[76:79], v[170:173], v[228:231], v[76:79]
	v_mfma_f32_16x16x32_bf16 v[72:75], v[178:181], v[228:231], v[72:75]
	v_mfma_f32_16x16x32_bf16 v[68:71], v[170:173], v[236:239], v[68:71]
	v_mfma_f32_16x16x32_bf16 v[64:67], v[178:181], v[236:239], v[64:67]
	v_mfma_f32_16x16x32_bf16 v[92:95], v[174:177], v[196:199], v[92:95]
	v_mfma_f32_16x16x32_bf16 v[88:91], v[188:191], v[196:199], v[88:91]
	v_mfma_f32_16x16x32_bf16 v[84:87], v[174:177], v[224:227], v[84:87]
	v_mfma_f32_16x16x32_bf16 v[80:83], v[188:191], v[224:227], v[80:83]
	v_mfma_f32_16x16x32_bf16 v[76:79], v[174:177], v[232:235], v[76:79]
	v_mfma_f32_16x16x32_bf16 v[72:75], v[188:191], v[232:235], v[72:75]
	v_mfma_f32_16x16x32_bf16 v[68:71], v[174:177], v[240:243], v[68:71]
	v_mfma_f32_16x16x32_bf16 v[64:67], v[188:191], v[240:243], v[64:67]
	s_setprio 0
	s_barrier
	s_add_i32 s26, s26, s40
	v_lshl_add_u64 v[244:245], v[204:205], 0, v[132:133]
	s_mov_b32 m0, s26
	ds_read_b128 v[192:195], v149 offset:16384
	ds_read_b128 v[196:199], v149 offset:17408
	ds_read_b128 v[200:203], v149 offset:18432
	ds_read_b128 v[224:227], v149 offset:19456
	ds_read_b128 v[228:231], v149 offset:20480
	ds_read_b128 v[232:235], v149 offset:21504
	ds_read_b128 v[236:239], v149 offset:22528
	ds_read_b128 v[240:243], v149 offset:23552
	global_load_lds_dwordx4 v[244:245], off
	v_lshl_add_u64 v[246:247], v[204:205], 0, v[136:137]
	s_add_i32 m0, s26, 0x2000
	v_lshl_add_u64 v[204:205], v[204:205], 0, s[58:59]
	s_add_i32 s9, s9, s40
	global_load_lds_dwordx4 v[246:247], off
	v_lshl_add_u64 v[248:249], v[204:205], 0, v[132:133]
	s_mov_b32 m0, s9
	v_lshl_add_u64 v[204:205], v[204:205], 0, v[136:137]
	global_load_lds_dwordx4 v[248:249], off
	s_add_i32 m0, s9, 0x2000
	v_lshl_add_u64 v[250:251], s[2:3], 0, v[130:131]
	global_load_lds_dwordx4 v[204:205], off
	s_mov_b32 m0, s41
	v_lshl_add_u64 v[218:219], s[2:3], 0, v[134:135]
	global_load_lds_dwordx4 v[250:251], off
	s_mov_b32 m0, s49
	s_nop 0
	global_load_lds_dwordx4 v[218:219], off
	s_waitcnt vmcnt(8)
	s_waitcnt lgkmcnt(0)
	s_waitcnt lgkmcnt(0)
	s_barrier
; #define PG8_STAGE(bufoff, gbase, voff) do { _Pragma("unroll") for (int _i = 0; _i < 2; ++_i) \
;         __builtin_amdgcn_global_load_lds((const unsigned*)((const char*)(gbase) + (voff)[_i]), (LAS unsigned*)(lds + (bufoff) + ldsw + _i * 8192), 16, 0, 0); } while (0)
; #define PG8_LDA(dst, b, h) do { _Pragma("unroll") for (int m = 0; m < 4; ++m) _Pragma("unroll") for (int k = 0; k < 2; ++k) dst[m][k] = *(const LAS bf16x8*)(lds + PG8_SA(b, h) + aoff + m * 2048 + k * 1024); } while (0)
; #define PG8_LDB(dst, b, h) do { _Pragma("unroll") for (int n = 0; n < 2; ++n) _Pragma("unroll") for (int k = 0; k < 2; ++k) dst[n][k] = *(const LAS bf16x8*)(lds + PG8_SB(b, h) + boff + n * 2048 + k * 1024); } while (0)
; #define PG8_MMA(ai, bj, At, Bt) do { __builtin_amdgcn_s_setprio(1); _Pragma("unroll") for (int m = 0; m < 4; ++m) _Pragma("unroll") for (int n = 0; n < 2; ++n) _Pragma("unroll") for (int k = 0; k < 2; ++k) \
;         acc[ai][bj][m][n] = __builtin_amdgcn_mfma_f32_16x16x32_bf16(Bt[n][k], At[m][k], acc[ai][bj][m][n], 0, 0, 0); __builtin_amdgcn_s_setprio(0); } while (0)
; #define PG8_WAIT_V(n) asm volatile("s_waitcnt vmcnt(" #n ")" ::: "memory")
; #define PG8_WAIT_L(n) asm volatile("s_waitcnt lgkmcnt(" #n ")" ::: "memory")
; #define PG8_BAR __builtin_amdgcn_s_barrier()
; #define PG8_SCHED __builtin_amdgcn_sched_barrier(0)
;     ...
;             PG8_WAIT_V(8); PG8_WAIT_L(0); PG8_BAR; PG8_MMA(1, 0, At, B0); PG8_MMA(1, 1, At, B1); PG8_BAR; PG8_SCHED;
;             PG8_LDB(B0, 1, 0); PG8_LDB(B1, 1, 1); PG8_SCHED; PG8_LDA(At, 1, 0); PG8_STAGE(PG8_SA(0, 1), a2 + hstepA, voffA);
;             PG8_WAIT_V(8); PG8_WAIT_L(0); PG8_BAR; PG8_MMA(0, 0, At, B0); PG8_MMA(0, 1, At, B1); PG8_BAR; PG8_SCHED;
	s_setprio 1
	v_mfma_f32_16x16x32_bf16 v[60:63], v[154:157], v[192:195], v[60:63]
	v_mfma_f32_16x16x32_bf16 v[56:59], v[162:165], v[192:195], v[56:59]
	v_mfma_f32_16x16x32_bf16 v[52:55], v[154:157], v[200:203], v[52:55]
	v_mfma_f32_16x16x32_bf16 v[48:51], v[162:165], v[200:203], v[48:51]
	v_mfma_f32_16x16x32_bf16 v[44:47], v[154:157], v[228:231], v[44:47]
	v_mfma_f32_16x16x32_bf16 v[40:43], v[162:165], v[228:231], v[40:43]
	v_mfma_f32_16x16x32_bf16 v[36:39], v[154:157], v[236:239], v[36:39]
	v_mfma_f32_16x16x32_bf16 v[32:35], v[162:165], v[236:239], v[32:35]
	v_mfma_f32_16x16x32_bf16 v[60:63], v[158:161], v[196:199], v[60:63]
	v_mfma_f32_16x16x32_bf16 v[56:59], v[166:169], v[196:199], v[56:59]
	v_mfma_f32_16x16x32_bf16 v[52:55], v[158:161], v[224:227], v[52:55]
	v_mfma_f32_16x16x32_bf16 v[48:51], v[166:169], v[224:227], v[48:51]
	v_mfma_f32_16x16x32_bf16 v[44:47], v[158:161], v[232:235], v[44:47]
	v_mfma_f32_16x16x32_bf16 v[40:43], v[166:169], v[232:235], v[40:43]
	v_mfma_f32_16x16x32_bf16 v[36:39], v[158:161], v[240:243], v[36:39]
	v_mfma_f32_16x16x32_bf16 v[32:35], v[166:169], v[240:243], v[32:35]
	s_setprio 0
	s_setprio 1
	v_mfma_f32_16x16x32_bf16 v[28:31], v[170:173], v[192:195], v[28:31]
	v_mfma_f32_16x16x32_bf16 v[24:27], v[178:181], v[192:195], v[24:27]
	v_mfma_f32_16x16x32_bf16 v[20:23], v[170:173], v[200:203], v[20:23]
	v_mfma_f32_16x16x32_bf16 v[16:19], v[178:181], v[200:203], v[16:19]
	v_mfma_f32_16x16x32_bf16 v[12:15], v[170:173], v[228:231], v[12:15]
	v_mfma_f32_16x16x32_bf16 v[8:11], v[178:181], v[228:231], v[8:11]
	v_mfma_f32_16x16x32_bf16 v[4:7], v[170:173], v[236:239], v[4:7]
	v_mfma_f32_16x16x32_bf16 v[0:3], v[178:181], v[236:239], v[0:3]
	v_mfma_f32_16x16x32_bf16 v[28:31], v[174:177], v[196:199], v[28:31]
	v_mfma_f32_16x16x32_bf16 v[24:27], v[188:191], v[196:199], v[24:27]
	v_mfma_f32_16x16x32_bf16 v[20:23], v[174:177], v[224:227], v[20:23]
	v_mfma_f32_16x16x32_bf16 v[16:19], v[188:191], v[224:227], v[16:19]
	v_mfma_f32_16x16x32_bf16 v[12:15], v[174:177], v[232:235], v[12:15]
	v_mfma_f32_16x16x32_bf16 v[8:11], v[188:191], v[232:235], v[8:11]
	v_mfma_f32_16x16x32_bf16 v[4:7], v[174:177], v[240:243], v[4:7]
	v_mfma_f32_16x16x32_bf16 v[0:3], v[188:191], v[240:243], v[0:3]
	s_setprio 0
	s_barrier
	s_add_i32 s9, 0, 0x18000
	v_add_u32_e32 v153, s9, v148
	s_add_i32 s26, 0, 0x1c000
	ds_read_b128 v[154:157], v153
	ds_read_b128 v[158:161], v153 offset:1024
	ds_read_b128 v[162:165], v153 offset:2048
	ds_read_b128 v[166:169], v153 offset:3072
	v_add_u32_e32 v153, s26, v148
	ds_read_b128 v[170:173], v153
	ds_read_b128 v[174:177], v153 offset:1024
	ds_read_b128 v[178:181], v153 offset:2048
	ds_read_b128 v[188:191], v153 offset:3072
	s_add_u32 s2, s2, s58
	s_addc_u32 s3, s3, 0
	s_mov_b32 m0, s10
	v_lshl_add_u64 v[212:213], s[2:3], 0, v[130:131]
	ds_read_b128 v[192:195], v149 offset:32768
	ds_read_b128 v[196:199], v149 offset:33792
	ds_read_b128 v[200:203], v149 offset:34816
	ds_read_b128 v[224:227], v149 offset:35840
	ds_read_b128 v[228:231], v149 offset:36864
	ds_read_b128 v[232:235], v149 offset:37888
	ds_read_b128 v[236:239], v149 offset:38912
	ds_read_b128 v[240:243], v149 offset:39936
	global_load_lds_dwordx4 v[212:213], off
	v_lshl_add_u64 v[212:213], s[2:3], 0, v[134:135]
	s_mov_b32 m0, s11
	s_nop 0
	global_load_lds_dwordx4 v[212:213], off
	s_waitcnt vmcnt(8)
	s_waitcnt lgkmcnt(0)
	s_waitcnt lgkmcnt(0)
	s_barrier
	s_setprio 1
	v_mfma_f32_16x16x32_bf16 v[124:127], v[154:157], v[192:195], v[124:127]
	v_mfma_f32_16x16x32_bf16 v[120:123], v[162:165], v[192:195], v[120:123]
	v_mfma_f32_16x16x32_bf16 v[116:119], v[154:157], v[200:203], v[116:119]
	v_mfma_f32_16x16x32_bf16 v[112:115], v[162:165], v[200:203], v[112:115]
	v_mfma_f32_16x16x32_bf16 v[108:111], v[154:157], v[228:231], v[108:111]
	v_mfma_f32_16x16x32_bf16 v[104:107], v[162:165], v[228:231], v[104:107]
	v_mfma_f32_16x16x32_bf16 v[100:103], v[154:157], v[236:239], v[100:103]
	v_mfma_f32_16x16x32_bf16 v[96:99], v[162:165], v[236:239], v[96:99]
	v_mfma_f32_16x16x32_bf16 v[124:127], v[158:161], v[196:199], v[124:127]
	v_mfma_f32_16x16x32_bf16 v[120:123], v[166:169], v[196:199], v[120:123]
	v_mfma_f32_16x16x32_bf16 v[116:119], v[158:161], v[224:227], v[116:119]
	v_mfma_f32_16x16x32_bf16 v[112:115], v[166:169], v[224:227], v[112:115]
	v_mfma_f32_16x16x32_bf16 v[108:111], v[158:161], v[232:235], v[108:111]
	v_mfma_f32_16x16x32_bf16 v[104:107], v[166:169], v[232:235], v[104:107]
	v_mfma_f32_16x16x32_bf16 v[100:103], v[158:161], v[240:243], v[100:103]
	v_mfma_f32_16x16x32_bf16 v[96:99], v[166:169], v[240:243], v[96:99]
	s_setprio 0
	s_setprio 1
	v_mfma_f32_16x16x32_bf16 v[92:95], v[170:173], v[192:195], v[92:95]
	v_mfma_f32_16x16x32_bf16 v[88:91], v[178:181], v[192:195], v[88:91]
	v_mfma_f32_16x16x32_bf16 v[84:87], v[170:173], v[200:203], v[84:87]
	v_mfma_f32_16x16x32_bf16 v[80:83], v[178:181], v[200:203], v[80:83]
	v_mfma_f32_16x16x32_bf16 v[76:79], v[170:173], v[228:231], v[76:79]
	v_mfma_f32_16x16x32_bf16 v[72:75], v[178:181], v[228:231], v[72:75]
	v_mfma_f32_16x16x32_bf16 v[68:71], v[170:173], v[236:239], v[68:71]
	v_mfma_f32_16x16x32_bf16 v[64:67], v[178:181], v[236:239], v[64:67]
	v_mfma_f32_16x16x32_bf16 v[92:95], v[174:177], v[196:199], v[92:95]
	v_mfma_f32_16x16x32_bf16 v[88:91], v[188:191], v[196:199], v[88:91]
	v_mfma_f32_16x16x32_bf16 v[84:87], v[174:177], v[224:227], v[84:87]
	v_mfma_f32_16x16x32_bf16 v[80:83], v[188:191], v[224:227], v[80:83]
	v_mfma_f32_16x16x32_bf16 v[76:79], v[174:177], v[232:235], v[76:79]
	v_mfma_f32_16x16x32_bf16 v[72:75], v[188:191], v[232:235], v[72:75]
	v_mfma_f32_16x16x32_bf16 v[68:71], v[174:177], v[240:243], v[68:71]
	v_mfma_f32_16x16x32_bf16 v[64:67], v[188:191], v[240:243], v[64:67]
	s_setprio 0
	s_barrier
; #define PG8_STAGE(bufoff, gbase, voff) do { _Pragma("unroll") for (int _i = 0; _i < 2; ++_i) \
;         __builtin_amdgcn_global_load_lds((const unsigned*)((const char*)(gbase) + (voff)[_i]), (LAS unsigned*)(lds + (bufoff) + ldsw + _i * 8192), 16, 0, 0); } while (0)
; #define PG8_LDA(dst, b, h) do { _Pragma("unroll") for (int m = 0; m < 4; ++m) _Pragma("unroll") for (int k = 0; k < 2; ++k) dst[m][k] = *(const LAS bf16x8*)(lds + PG8_SA(b, h) + aoff + m * 2048 + k * 1024); } while (0)
; #define PG8_MMA(ai, bj, At, Bt) do { __builtin_amdgcn_s_setprio(1); _Pragma("unroll") for (int m = 0; m < 4; ++m) _Pragma("unroll") for (int n = 0; n < 2; ++n) _Pragma("unroll") for (int k = 0; k < 2; ++k) \
;         acc[ai][bj][m][n] = __builtin_amdgcn_mfma_f32_16x16x32_bf16(Bt[n][k], At[m][k], acc[ai][bj][m][n], 0, 0, 0); __builtin_amdgcn_s_setprio(0); } while (0)
; #define PG8_WAIT_V(n) asm volatile("s_waitcnt vmcnt(" #n ")" ::: "memory")
; #define PG8_WAIT_L(n) asm volatile("s_waitcnt lgkmcnt(" #n ")" ::: "memory")
; #define PG8_BAR __builtin_amdgcn_s_barrier()
; #define PG8_SCHED __builtin_amdgcn_sched_barrier(0)
;     ...
;             PG8_LDA(At, 1, 1); PG8_STAGE(PG8_SB(1, 0), b3, voffB); PG8_STAGE(PG8_SB(1, 1), b3 + hstepB, voffB); PG8_STAGE(PG8_SA(1, 0), a3, voffA);
;             PG8_WAIT_V(8); PG8_WAIT_L(0); PG8_BAR; PG8_MMA(1, 0, At, B0); PG8_MMA(1, 1, At, B1); PG8_BAR; PG8_SCHED;
;         }
;         if (wr == 0) PG8_BAR;
	s_add_i32 s2, s9, s40
	v_lshl_add_u64 v[212:213], v[244:245], 0, s[70:71]
	s_mov_b32 m0, s2
	ds_read_b128 v[192:195], v149 offset:49152
	ds_read_b128 v[196:199], v149 offset:50176
	ds_read_b128 v[200:203], v149 offset:51200
	ds_read_b128 v[224:227], v149 offset:52224
	ds_read_b128 v[228:231], v149 offset:53248
	ds_read_b128 v[232:235], v149 offset:54272
	ds_read_b128 v[236:239], v149 offset:55296
	ds_read_b128 v[240:243], v149 offset:56320
	global_load_lds_dwordx4 v[212:213], off
	v_lshl_add_u64 v[212:213], v[246:247], 0, s[70:71]
	s_add_i32 m0, s2, 0x2000
	s_add_i32 s2, s26, s40
	global_load_lds_dwordx4 v[212:213], off
	v_lshl_add_u64 v[212:213], v[248:249], 0, s[70:71]
	s_mov_b32 m0, s2
	v_lshl_add_u64 v[204:205], v[204:205], 0, s[70:71]
	global_load_lds_dwordx4 v[212:213], off
	s_add_i32 m0, s2, 0x2000
	s_nop 0
	global_load_lds_dwordx4 v[204:205], off
	v_lshl_add_u64 v[204:205], v[250:251], 0, s[70:71]
	s_mov_b32 m0, s51
	s_nop 0
	global_load_lds_dwordx4 v[204:205], off
	v_lshl_add_u64 v[204:205], v[218:219], 0, s[70:71]
	s_mov_b32 m0, s64
	s_nop 0
	global_load_lds_dwordx4 v[204:205], off
	s_waitcnt vmcnt(8)
	s_waitcnt lgkmcnt(0)
	s_waitcnt lgkmcnt(0)
	s_barrier
	s_setprio 1
	v_mfma_f32_16x16x32_bf16 v[60:63], v[154:157], v[192:195], v[60:63]
	v_mfma_f32_16x16x32_bf16 v[56:59], v[162:165], v[192:195], v[56:59]
	v_mfma_f32_16x16x32_bf16 v[52:55], v[154:157], v[200:203], v[52:55]
	v_mfma_f32_16x16x32_bf16 v[48:51], v[162:165], v[200:203], v[48:51]
	v_mfma_f32_16x16x32_bf16 v[44:47], v[154:157], v[228:231], v[44:47]
	v_mfma_f32_16x16x32_bf16 v[40:43], v[162:165], v[228:231], v[40:43]
	v_mfma_f32_16x16x32_bf16 v[36:39], v[154:157], v[236:239], v[36:39]
	v_mfma_f32_16x16x32_bf16 v[32:35], v[162:165], v[236:239], v[32:35]
	v_mfma_f32_16x16x32_bf16 v[60:63], v[158:161], v[196:199], v[60:63]
	v_mfma_f32_16x16x32_bf16 v[56:59], v[166:169], v[196:199], v[56:59]
	v_mfma_f32_16x16x32_bf16 v[52:55], v[158:161], v[224:227], v[52:55]
	v_mfma_f32_16x16x32_bf16 v[48:51], v[166:169], v[224:227], v[48:51]
	v_mfma_f32_16x16x32_bf16 v[44:47], v[158:161], v[232:235], v[44:47]
	v_mfma_f32_16x16x32_bf16 v[40:43], v[166:169], v[232:235], v[40:43]
	v_mfma_f32_16x16x32_bf16 v[36:39], v[158:161], v[240:243], v[36:39]
	v_mfma_f32_16x16x32_bf16 v[32:35], v[166:169], v[240:243], v[32:35]
	s_setprio 0
	s_setprio 1
	v_mfma_f32_16x16x32_bf16 v[28:31], v[170:173], v[192:195], v[28:31]
	v_mfma_f32_16x16x32_bf16 v[24:27], v[178:181], v[192:195], v[24:27]
	v_mfma_f32_16x16x32_bf16 v[20:23], v[170:173], v[200:203], v[20:23]
	v_mfma_f32_16x16x32_bf16 v[16:19], v[178:181], v[200:203], v[16:19]
	v_mfma_f32_16x16x32_bf16 v[12:15], v[170:173], v[228:231], v[12:15]
	v_mfma_f32_16x16x32_bf16 v[8:11], v[178:181], v[228:231], v[8:11]
	v_mfma_f32_16x16x32_bf16 v[4:7], v[170:173], v[236:239], v[4:7]
	v_mfma_f32_16x16x32_bf16 v[0:3], v[178:181], v[236:239], v[0:3]
	v_mfma_f32_16x16x32_bf16 v[28:31], v[174:177], v[196:199], v[28:31]
	v_mfma_f32_16x16x32_bf16 v[24:27], v[188:191], v[196:199], v[24:27]
	v_mfma_f32_16x16x32_bf16 v[20:23], v[174:177], v[224:227], v[20:23]
	v_mfma_f32_16x16x32_bf16 v[16:19], v[188:191], v[224:227], v[16:19]
	v_mfma_f32_16x16x32_bf16 v[12:15], v[174:177], v[232:235], v[12:15]
	v_mfma_f32_16x16x32_bf16 v[8:11], v[188:191], v[232:235], v[8:11]
	v_mfma_f32_16x16x32_bf16 v[4:7], v[174:177], v[240:243], v[4:7]
	v_mfma_f32_16x16x32_bf16 v[0:3], v[188:191], v[240:243], v[0:3]
	s_setprio 0
	s_barrier
	s_add_u32 s0, s0, 0x100
	s_addc_u32 s1, s1, 0
	v_lshl_add_u64 v[146:147], v[146:147], 0, s[94:95]
	v_lshl_add_u64 v[144:145], v[144:145], 0, s[94:95]
	s_cmp_ge_u32 s8, s48
	s_mov_b32 s2, s8
	s_cbranch_scc0 .LBB0_416
	v_readlane_b32 s0, v254, 45
	v_readlane_b32 s1, v254, 46
	s_and_b64 vcc, exec, s[0:1]
	s_cbranch_vccz .LBB0_419
	s_barrier
